# DA attention loop trimmed: K/V addresses carry the workspace base, always-true exec predicates and redundant drains removed, one LDS wait per two MFMAs
# speedup vs baseline: 1.0186x; 1.0171x over previous
; #define LAS __attribute__((address_space(3)))
; DI float ex2(float x) { return __builtin_amdgcn_exp2f(x); }
; template <int MODE>
; DI void attn_unit(LAS unsigned char* lds, const bf16_t* Qg, int ldq, const bf16_t* Kg, int ldk, const bf16_t* VTg, int ldvt, bf16_t* Og, int ldo,
;                   int q0, int NT, const float* gout, const float* relb, float lam, float osc, const float* qgain) {
;     ...
;                 float rs = 0.f;
; #pragma unroll
;                 for (int i = 0; i < 16; ++i) { p0[i] = ex2(p0[i]); p1[i] = ex2(p1[i]); rs += p0[i] + p1[i]; }
;                 lrun += rs;
;             } else {
;                 f32x16 L0, L1;
;                 const bool diag = (NT - 1 - t) == TD;
;                 sb_prep(p0, L0, key0 + 4 * hi, qrow, diag); sb_prep(p1, L1, key0 + 32 + 4 * hi, qrow, diag);
;                 float own[8], par[8];
; #pragma unroll
;                 for (int g = 0; g < 4; ++g) { own[g] = (L0[4 * g] + L0[4 * g + 1]) + (L0[4 * g + 2] + L0[4 * g + 3]); own[4 + g] = (L1[4 * g] + L1[4 * g + 1]) + (L1[4 * g + 2] + L1[4 * g + 3]); }
; #pragma unroll
;                 for (int g = 0; g < 8; ++g) par[g] = shx(own[g], 32, lane);
;                 float so = 0.f, sp2 = 0.f;
; #pragma unroll
;                 for (int g = 7; g >= 0; --g) {
;                     const float SG = R + so + sp2 + (hi == 0 ? par[g] : 0.f);
;                     float w = 0.f;
; #pragma unroll
;                     for (int e = 3; e >= 0; --e) { const int idx = 4 * (g & 3) + e;
;                         if (g >= 4) { p1[idx] = ex2(p1[idx] + SG + w); w += L1[idx]; } else { p0[idx] = ex2(p0[idx] + SG + w); w += L0[idx]; } }
;                     so += own[g]; sp2 += par[g];
;                 }
;                 R += so + sp2;
;             }
; #pragma unroll
;             for (int j = 0; j < 4; ++j) { pk[0][j] = cvtpk(p0[2 * j], p0[2 * j + 1]); pk[1][j] = cvtpk(p0[8 + 2 * j], p0[8 + 2 * j + 1]);
;                 pk[2][j] = cvtpk(p1[2 * j], p1[2 * j + 1]); pk[3][j] = cvtpk(p1[8 + 2 * j], p1[8 + 2 * j + 1]); }
;             if (!skew) pvdo(vcur, pk);
;         }
;         if (MODE == 2 && SB_EARLY) { if (lane == 0) ((LAS unsigned*)(lds + FLG))[cur * 8 + wid] = (!active || __any(R > -150.f)) ? 1u : 0u; }
;         if (t + 1 < NT) AT_LSTORE(cur ^ 1, vnext);
;         __syncthreads();
;         vcur = vnext;
.LBB0_179:
	s_or_b64 exec, exec, s[10:11]
	v_add_f32_e32 v157, v161, v157
	v_pk_add_f32 v[156:157], v[156:157], v[0:1]
	v_add_f32_e32 v155, v155, v153
	v_pk_add_f32 v[156:157], v[156:157], v[156:157] op_sel_hi:[0,1]
	v_mov_b32_e32 v153, v157
	v_pk_add_f32 v[152:153], v[154:155], v[152:153]
	v_add_f32_e32 v115, v115, v113
	v_pk_add_f32 v[152:153], v[152:153], v[152:153] op_sel_hi:[0,1]
	v_mov_b32_e32 v113, v153
	v_pk_add_f32 v[112:113], v[114:115], v[112:113]
	v_add_f32_e32 v111, v111, v109
	v_pk_add_f32 v[112:113], v[112:113], v[112:113] op_sel_hi:[0,1]
	v_mov_b32_e32 v109, v113
	v_pk_add_f32 v[108:109], v[110:111], v[108:109]
	v_add_f32_e32 v107, v160, v81
	v_pk_add_f32 v[108:109], v[108:109], v[108:109] op_sel_hi:[0,1]
	v_mov_b32_e32 v105, v109
	v_pk_add_f32 v[104:105], v[106:107], v[104:105]
	v_add_f32_e32 v81, v79, v77
	v_pk_add_f32 v[104:105], v[104:105], v[104:105] op_sel_hi:[0,1]
	v_mov_b32_e32 v79, v105
	v_pk_add_f32 v[78:79], v[80:81], v[78:79]
	v_add_f32_e32 v77, v75, v73
	v_pk_add_f32 v[78:79], v[78:79], v[78:79] op_sel_hi:[0,1]
	v_mov_b32_e32 v75, v79
	v_pk_add_f32 v[74:75], v[76:77], v[74:75]
	s_mov_b32 s2, 0xcc00
	v_pk_add_f32 v[74:75], v[74:75], v[74:75] op_sel_hi:[0,1]
	v_add_f32_e32 v73, v71, v69
	v_mov_b32_e32 v71, v75
	v_add3_u32 v0, v185, v186, s2
	v_pk_add_f32 v[70:71], v[72:73], v[70:71]
	s_waitcnt vmcnt(0)
	ds_write2_b64 v0, v[140:141], v[142:143] offset1:1
	v_add3_u32 v0, v185, v187, s2
	v_pk_add_f32 v[70:71], v[70:71], v[70:71] op_sel_hi:[0,1]
	ds_write2_b64 v0, v[144:145], v[146:147] offset1:1
	v_add_u32_e32 v0, v82, v83
	v_ashrrev_i32_e32 v70, 4, v0
	v_and_b32_e32 v0, -16, v0
	v_mov_b32_e32 v69, v71
	v_sub_u32_e32 v0, v82, v0
	v_pk_add_f32 v[152:153], v[68:69], 0 op_sel_hi:[1,0]
	v_lshlrev_b32_e32 v72, 3, v0
	v_lshlrev_b32_e32 v193, 4, v0
	v_add_u32_e32 v0, s21, v150
	v_lshlrev_b32_e32 v69, 2, v159
	s_lshl_b32 s12, s29, 1
	s_lshr_b32 s19, s24, 6
	v_sub_u32_e32 v0, v0, v69
	s_lshl_b32 s2, s27, 7
	s_add_i32 s14, s12, 2
	s_add_i32 s18, s19, 1
	s_addk_i32 s24, 0xff41
	v_subrev_u32_e32 v0, s2, v0
	s_lshl_b32 s25, s29, 9
	s_lshl_b64 s[2:3], s[16:17], 12
	s_add_u32 s2, s20, s2
	s_addc_u32 s3, 0, s3
	v_subrev_u32_e32 v0, s25, v0
	s_add_u32 s2, s2, 0x18000100
	v_add_u32_e32 v194, 0, v0
	s_addc_u32 s3, s3, 0
	v_and_b32_e32 v0, 7, v82
	v_lshl_add_u64 v[76:77], s[2:3], 0, v[100:101]
	v_lshlrev_b32_e32 v0, 4, v0
	v_lshl_add_u64 v[154:155], v[76:77], 0, v[0:1]
	v_lshl_add_u64 v[76:77], s[2:3], 0, v[102:103]
	s_add_u32 s2, s8, s28
	s_addc_u32 s3, s9, 0
	v_mul_u32_u24_e32 v191, 0x88, v159
	v_ashrrev_i32_e32 v159, 31, v158
	s_add_u32 s2, s2, 0x8080400
	v_ashrrev_i32_e32 v71, 31, v70
	v_lshlrev_b32_e32 v74, 3, v162
	v_mul_lo_u32 v192, v70, s56
	v_lshl_add_u64 v[156:157], v[76:77], 0, v[0:1]
	v_lshlrev_b64 v[76:77], 12, v[158:159]
	s_addc_u32 s3, s3, 0
	v_lshlrev_b64 v[70:71], 12, v[70:71]
	v_sub_f32_e32 v68, v66, v152
	v_ashrrev_i32_e32 v73, 31, v72
	v_ashrrev_i32_e32 v75, 31, v74
	v_lshl_add_u64 v[76:77], s[2:3], 0, v[76:77]
	v_lshl_add_u64 v[70:71], s[2:3], 0, v[70:71]
	s_mov_b32 s13, 1
	s_mov_b32 s15, 2
	s_mov_b32 s21, s29
	v_lshl_add_u64 v[158:159], v[74:75], 1, v[76:77]
	v_lshl_add_u64 v[160:161], v[72:73], 1, v[70:71]
	s_movk_i32 s28, 0xff00
	s_mov_b32 s29, 64
	v_mov_b32_e32 v69, v68
	v_mov_b32_e32 v70, v68
	v_mov_b32_e32 v71, v68
	v_mov_b32_e32 v72, v68
	v_mov_b32_e32 v73, v68
	v_mov_b32_e32 v74, v68
	v_mov_b32_e32 v75, v68
	v_mov_b32_e32 v76, v68
	v_mov_b32_e32 v77, v68
	v_mov_b32_e32 v78, v68
	v_mov_b32_e32 v79, v68
	v_mov_b32_e32 v80, v68
	v_mov_b32_e32 v81, v68
	v_mov_b32_e32 v82, v68
	v_mov_b32_e32 v83, v68
	v_readlane_b32 s2, v253, 40
	v_readlane_b32 s3, v253, 41
	s_nop 1
	v_lshl_add_u64 v[154:155], s[2:3], 0, v[154:155]
	v_lshl_add_u64 v[156:157], s[2:3], 0, v[156:157]
	v_lshl_add_u64 v[158:159], s[2:3], 0, v[158:159]
	v_lshl_add_u64 v[160:161], s[2:3], 0, v[160:161]
	s_waitcnt lgkmcnt(0)
	s_barrier
	s_branch .LBB0_182
.LBB0_180:
	s_mul_i32 s2, s13, 0x4400
	v_add_u32_e32 v0, s2, v185
	s_mov_b32 s2, 0x8800
	v_add3_u32 v100, v0, v186, s2
	v_add3_u32 v0, v0, v187, s2
	ds_write2_b64 v100, v[140:141], v[142:143] offset1:1
	ds_write2_b64 v0, v[144:145], v[146:147] offset1:1

; template <int MODE>
; DI void attn_unit(LAS unsigned char* lds, const bf16_t* Qg, int ldq, const bf16_t* Kg, int ldk, const bf16_t* VTg, int ldvt, bf16_t* Og, int ldo,
;                   int q0, int NT, const float* gout, const float* relb, float lam, float osc, const float* qgain) {
;     ...
;     auto pvdo = [&](const int vbi, const u32x4 (&pp)[4]) {
;         const LAS unsigned char* Vb = lds + VB0 + vbi * VBSZ + (r32 + (MODE == 2 ? mm * 64 : 0)) * VSTR + hi * 8;
; #pragma unroll
;         for (int d = 0; d < NDB; ++d)
; #pragma unroll
;             for (int ks = 0; ks < 4; ++ks) { const int kb = 32 * (ks >> 1) + 16 * (ks & 1);
;                 const s16x4 lo = *(const LAS s16x4*)(Vb + d * 32 * VSTR + kb * 2), hh = *(const LAS s16x4*)(Vb + d * 32 * VSTR + kb * 2 + 16);
;                 const bf16x8 vf = __builtin_shufflevector(lo, hh, 0, 1, 2, 3, 4, 5, 6, 7);
;                 o[d] = MFMA32(vf, __builtin_bit_cast(bf16x8, pp[ks]), o[d]); }
;     };
;     int vcur = 0;
;     for (int t = 0; t < NT; ++t) {
;         const int cur = t & 1;
;         const int vnext = vcur == 2 ? 0 : vcur + 1, vprev = vcur == 0 ? 2 : vcur - 1;
;         if (MODE == 2 && SB_EARLY && t > 0) {
;             const LAS unsigned* fl = (const LAS unsigned*)(lds + FLG) + ((t - 1) & 1) * 8; unsigned any = 0;
; #pragma unroll
;             for (int w = 0; w < 8; ++w) any |= fl[w];
;             if (any == 0u) break;
;         }
;         if (t + 1 < NT) AT_GLOAD(AT_KEY0(t + 1));
;         const int key0 = AT_KEY0(t);
;         bool active;
;         if (MODE == 2) active = (NT - 1 - t) <= TD; else active = t < ntw;
;         bool alive = true;
;         if (MODE == 2) alive = !active || __any(R > -150.f);
;         if (skew && t >= 1 && (t - 1) < ntw) pvdo(vprev, pk);
;         if (active && alive) {
;             const LAS unsigned char* Kb = lds + (cur ? KB1 : KB0) + r32 * KSTR + mm * 128 + hi * 16;
;             f32x16 p0, p1;
; #pragma unroll
;             for (int s = 0; s < NS; ++s) { const bf16x8 a0 = *(const LAS bf16x8*)(Kb + s * 32), a1 = *(const LAS bf16x8*)(Kb + 32 * KSTR + s * 32);
;                 if (s == 0) { p0 = MFMA32(a0, qf[0], negm); p1 = MFMA32(a1, qf[0], negm); } else { p0 = MFMA32(a0, qf[s], p0); p1 = MFMA32(a1, qf[s], p1); } }
;             if (MODE != 2) {
;                 if (MODE == 0) {
;                     const int qmin = q0 + 32 * rg;
.LBB0_182:
	s_cmp_lt_u32 s15, s14
	s_cselect_b64 s[8:9], -1, 0
	s_cmp_ge_u32 s15, s14
	s_cbranch_scc1 .LBB0_188
	global_load_dwordx4 v[132:135], v[160:161], off
.LBB0_185:
	global_load_dwordx4 v[136:139], v[158:159], off
.LBB0_187:
	global_load_dwordx4 v[140:143], v[154:155], off
	global_load_dwordx4 v[144:147], v[156:157], off
.LBB0_188:
	s_add_i32 s2, s15, -1
	s_cmp_le_u32 s2, s18
	s_cselect_b64 s[10:11], -1, 0
	s_and_b64 s[10:11], s[0:1], s[10:11]
	s_andn2_b64 vcc, exec, s[10:11]
	s_cbranch_vccnz .LBB0_190
	s_mul_i32 s3, s13, 0x4400
	s_addk_i32 s3, 0xbc00
	s_cmp_lg_u32 s13, 0
	s_cselect_b32 s3, s3, 0x8800
	v_add_u32_e32 v0, s3, v67
	v_add_u32_e32 v236, 0x8800, v0
	v_add_u32_e32 v237, 0x9800, v0
	v_add_u32_e32 v238, 0xa800, v0
	v_add_u32_e32 v239, 0xb800, v0
	ds_read2_b64 v[212:215], v236 offset1:2
	ds_read2_b64 v[216:219], v236 offset0:4 offset1:6
	ds_read2_b64 v[220:223], v236 offset0:8 offset1:10
	ds_read2_b64 v[224:227], v236 offset0:12 offset1:14
	s_waitcnt lgkmcnt(2)
	v_mfma_f32_32x32x16_bf16 v[50:65], v[212:215], v[96:99], v[50:65]
	v_mfma_f32_32x32x16_bf16 v[50:65], v[216:219], v[92:95], v[50:65]
	ds_read2_b64 v[212:215], v237 offset0:32 offset1:34
	ds_read2_b64 v[216:219], v237 offset0:36 offset1:38
	s_waitcnt lgkmcnt(2)
	v_mfma_f32_32x32x16_bf16 v[50:65], v[220:223], v[88:91], v[50:65]
	v_mfma_f32_32x32x16_bf16 v[50:65], v[224:227], v[84:87], v[50:65]
	ds_read2_b64 v[220:223], v237 offset0:40 offset1:42
	ds_read2_b64 v[224:227], v237 offset0:44 offset1:46
	s_waitcnt lgkmcnt(2)
	v_mfma_f32_32x32x16_bf16 v[34:49], v[212:215], v[96:99], v[34:49]
	v_mfma_f32_32x32x16_bf16 v[34:49], v[216:219], v[92:95], v[34:49]
	ds_read2_b64 v[212:215], v238 offset0:64 offset1:66
	ds_read2_b64 v[216:219], v238 offset0:68 offset1:70
	s_waitcnt lgkmcnt(2)
	v_mfma_f32_32x32x16_bf16 v[34:49], v[220:223], v[88:91], v[34:49]
	v_mfma_f32_32x32x16_bf16 v[34:49], v[224:227], v[84:87], v[34:49]
	ds_read2_b64 v[220:223], v238 offset0:72 offset1:74
	ds_read2_b64 v[224:227], v238 offset0:76 offset1:78
	s_waitcnt lgkmcnt(2)
	v_mfma_f32_32x32x16_bf16 v[18:33], v[212:215], v[96:99], v[18:33]
	v_mfma_f32_32x32x16_bf16 v[18:33], v[216:219], v[92:95], v[18:33]
	ds_read2_b64 v[212:215], v239 offset0:96 offset1:98
	ds_read2_b64 v[216:219], v239 offset0:100 offset1:102
	s_waitcnt lgkmcnt(2)
	v_mfma_f32_32x32x16_bf16 v[18:33], v[220:223], v[88:91], v[18:33]
	v_mfma_f32_32x32x16_bf16 v[18:33], v[224:227], v[84:87], v[18:33]
	ds_read2_b64 v[220:223], v239 offset0:104 offset1:106
	ds_read2_b64 v[224:227], v239 offset0:108 offset1:110
	s_waitcnt lgkmcnt(2)
	v_mfma_f32_32x32x16_bf16 v[2:17], v[212:215], v[96:99], v[2:17]
	v_mfma_f32_32x32x16_bf16 v[2:17], v[216:219], v[92:95], v[2:17]
	s_waitcnt lgkmcnt(0)
	v_mfma_f32_32x32x16_bf16 v[2:17], v[220:223], v[88:91], v[2:17]
	v_mfma_f32_32x32x16_bf16 v[2:17], v[224:227], v[84:87], v[2:17]
.LBB0_190:
	s_and_b32 s10, s2, 1
	s_cmp_gt_u32 s2, s19
	s_cbranch_scc1 .LBB0_198
	s_cmp_eq_u32 s10, 0
	s_cselect_b32 s2, 0, 0x4400
	v_add_u32_e32 v0, s2, v188
	ds_read_b128 v[196:199], v0
	ds_read_b128 v[200:203], v0 offset:8704
	ds_read_b128 v[204:207], v0 offset:32
	ds_read_b128 v[208:211], v0 offset:8736
	ds_read_b128 v[212:215], v0 offset:64
	ds_read_b128 v[216:219], v0 offset:8768
	ds_read_b128 v[220:223], v0 offset:96
	ds_read_b128 v[224:227], v0 offset:8800
	s_cmp_le_i32 s29, s24
	s_waitcnt lgkmcnt(6)
	v_mfma_f32_32x32x16_bf16 v[84:99], v[196:199], v[116:119], v[68:83]
	v_mfma_f32_32x32x16_bf16 v[100:115], v[200:203], v[116:119], v[68:83]
	s_waitcnt lgkmcnt(4)
	v_mfma_f32_32x32x16_bf16 v[84:99], v[204:207], v[120:123], v[84:99]
	v_mfma_f32_32x32x16_bf16 v[100:115], v[208:211], v[120:123], v[100:115]
	s_waitcnt lgkmcnt(2)
	v_mfma_f32_32x32x16_bf16 v[84:99], v[212:215], v[124:127], v[84:99]
	v_mfma_f32_32x32x16_bf16 v[100:115], v[216:219], v[124:127], v[100:115]
	s_waitcnt lgkmcnt(0)
	v_mfma_f32_32x32x16_bf16 v[84:99], v[220:223], v[128:131], v[84:99]
	v_mfma_f32_32x32x16_bf16 v[100:115], v[224:227], v[128:131], v[100:115]
	s_nop 1
	s_cbranch_scc1 .LBB0_193
	v_add_u32_e32 v0, s28, v194
	v_add_u32_e32 v162, 0x15a00, v0
	v_add_u32_e32 v164, 0x15a80, v0
	ds_read2_b32 v[162:163], v162 offset1:1
	ds_read2_b32 v[164:165], v164 offset1:1
	v_add_u32_e32 v166, 0x15a08, v0
	v_add_u32_e32 v168, 0x15a88, v0
	v_add_u32_e32 v170, 0x15a20, v0
	v_add_u32_e32 v172, 0x15aa0, v0
	v_add_u32_e32 v174, 0x15a28, v0
	v_add_u32_e32 v176, 0x15aa8, v0
	v_add_u32_e32 v178, 0x15a40, v0
	v_add_u32_e32 v195, 0x15ac0, v0
	ds_read2_b32 v[166:167], v166 offset1:1
	ds_read2_b32 v[168:169], v168 offset1:1
	ds_read2_b32 v[170:171], v170 offset1:1
	ds_read2_b32 v[172:173], v172 offset1:1
	ds_read2_b32 v[174:175], v174 offset1:1
	ds_read2_b32 v[176:177], v176 offset1:1
	ds_read2_b32 v[178:179], v178 offset1:1
	ds_read2_b32 v[196:197], v195 offset1:1
	v_add_u32_e32 v195, 0x15a48, v0
	v_add_u32_e32 v200, 0x15ac8, v0
	ds_read2_b32 v[198:199], v195 offset1:1
	ds_read2_b32 v[200:201], v200 offset1:1
	v_add_u32_e32 v195, 0x15a60, v0
	v_add_u32_e32 v204, 0x15ae0, v0
	ds_read2_b32 v[202:203], v195 offset1:1
	ds_read2_b32 v[204:205], v204 offset1:1
	v_add_u32_e32 v195, 0x15a68, v0
	v_add_u32_e32 v0, 0x15ae8, v0
	ds_read2_b32 v[208:209], v195 offset1:1
	s_waitcnt lgkmcnt(0)
	v_pk_add_f32 v[84:85], v[84:85], v[162:163]
	ds_read2_b32 v[162:163], v0 offset1:1
	v_pk_add_f32 v[96:97], v[96:97], v[202:203]
	v_pk_add_f32 v[94:95], v[94:95], v[198:199]
	v_pk_add_f32 v[98:99], v[98:99], v[208:209]
	v_pk_add_f32 v[92:93], v[92:93], v[178:179]
	v_pk_add_f32 v[90:91], v[90:91], v[174:175]
	v_pk_add_f32 v[88:89], v[88:89], v[170:171]
	v_pk_add_f32 v[86:87], v[86:87], v[166:167]
	s_waitcnt lgkmcnt(0)
	v_pk_add_f32 v[114:115], v[114:115], v[162:163]
	v_pk_add_f32 v[112:113], v[112:113], v[204:205]
	v_pk_add_f32 v[110:111], v[110:111], v[200:201]
	v_pk_add_f32 v[108:109], v[108:109], v[196:197]
	v_pk_add_f32 v[106:107], v[106:107], v[176:177]
	v_pk_add_f32 v[104:105], v[104:105], v[172:173]
	v_pk_add_f32 v[102:103], v[102:103], v[168:169]
	v_pk_add_f32 v[100:101], v[100:101], v[164:165]

; DI unsigned cvtpk(float lo, float hi) { f32x2_t v = {lo, hi}; bf16x2_t b = __builtin_convertvector(v, bf16x2_t); return __builtin_bit_cast(unsigned, b); }
; DI float shx(float v, int mask, int lane) { return __builtin_bit_cast(float, __builtin_amdgcn_ds_bpermute((lane ^ mask) << 2, __builtin_bit_cast(int, v))); }
; DI float ex2(float x) { return __builtin_amdgcn_exp2f(x); }
; template <int MODE>
; DI void attn_unit(LAS unsigned char* lds, const bf16_t* Qg, int ldq, const bf16_t* Kg, int ldk, const bf16_t* VTg, int ldvt, bf16_t* Og, int ldo,
;                   int q0, int NT, const float* gout, const float* relb, float lam, float osc, const float* qgain) {
;     ...
;                 float rs = 0.f;
; #pragma unroll
;                 for (int i = 0; i < 16; ++i) { p0[i] = ex2(p0[i]); p1[i] = ex2(p1[i]); rs += p0[i] + p1[i]; }
;                 lrun += rs;
;             } else {
;                 f32x16 L0, L1;
;                 const bool diag = (NT - 1 - t) == TD;
;                 sb_prep(p0, L0, key0 + 4 * hi, qrow, diag); sb_prep(p1, L1, key0 + 32 + 4 * hi, qrow, diag);
;                 float own[8], par[8];
; #pragma unroll
;                 for (int g = 0; g < 4; ++g) { own[g] = (L0[4 * g] + L0[4 * g + 1]) + (L0[4 * g + 2] + L0[4 * g + 3]); own[4 + g] = (L1[4 * g] + L1[4 * g + 1]) + (L1[4 * g + 2] + L1[4 * g + 3]); }
; #pragma unroll
;                 for (int g = 0; g < 8; ++g) par[g] = shx(own[g], 32, lane);
;                 float so = 0.f, sp2 = 0.f;
; #pragma unroll
;                 for (int g = 7; g >= 0; --g) {
;                     const float SG = R + so + sp2 + (hi == 0 ? par[g] : 0.f);
;                     float w = 0.f;
; #pragma unroll
;                     for (int e = 3; e >= 0; --e) { const int idx = 4 * (g & 3) + e;
;                         if (g >= 4) { p1[idx] = ex2(p1[idx] + SG + w); w += L1[idx]; } else { p0[idx] = ex2(p0[idx] + SG + w); w += L0[idx]; } }
;                     so += own[g]; sp2 += par[g];
;                 }
;                 R += so + sp2;
;             }
; #pragma unroll
;             for (int j = 0; j < 4; ++j) { pk[0][j] = cvtpk(p0[2 * j], p0[2 * j + 1]); pk[1][j] = cvtpk(p0[8 + 2 * j], p0[8 + 2 * j + 1]);
;                 pk[2][j] = cvtpk(p1[2 * j], p1[2 * j + 1]); pk[3][j] = cvtpk(p1[8 + 2 * j], p1[8 + 2 * j + 1]); }
;             if (!skew) pvdo(vcur, pk);
.LBB0_195:
	v_exp_f32_e32 v179, v84
	v_exp_f32_e32 v196, v100
	v_exp_f32_e32 v0, v85
	v_exp_f32_e32 v178, v101
	v_exp_f32_e32 v175, v86
	v_exp_f32_e32 v177, v102
	v_exp_f32_e32 v174, v87
	v_exp_f32_e32 v176, v103
	v_exp_f32_e32 v171, v88
	v_exp_f32_e32 v173, v104
	v_exp_f32_e32 v170, v89
	v_exp_f32_e32 v172, v105
	v_exp_f32_e32 v167, v90
	v_exp_f32_e32 v169, v106
	v_exp_f32_e32 v166, v91
	v_exp_f32_e32 v168, v107
	v_exp_f32_e32 v163, v92
	v_exp_f32_e32 v165, v108
	v_exp_f32_e32 v162, v93
	v_exp_f32_e32 v164, v109
	v_exp_f32_e32 v109, v94
	v_exp_f32_e32 v195, v110
	v_exp_f32_e32 v108, v95
	v_exp_f32_e32 v110, v111
	v_exp_f32_e32 v105, v96
	v_exp_f32_e32 v107, v112
	v_exp_f32_e32 v104, v97
	v_exp_f32_e32 v106, v113
	v_exp_f32_e32 v101, v98
	v_exp_f32_e32 v103, v114
	v_exp_f32_e32 v100, v99
	v_exp_f32_e32 v102, v115
	v_cvt_pk_bf16_f32 v96, v179, v0
	v_cvt_pk_bf16_f32 v92, v163, v162
	v_cvt_pk_bf16_f32 v88, v196, v178
	v_cvt_pk_bf16_f32 v84, v165, v164
	v_cvt_pk_bf16_f32 v97, v175, v174
	v_cvt_pk_bf16_f32 v93, v109, v108
	v_cvt_pk_bf16_f32 v89, v177, v176
	v_cvt_pk_bf16_f32 v85, v195, v110
	v_cvt_pk_bf16_f32 v98, v171, v170
	v_cvt_pk_bf16_f32 v94, v105, v104
	v_cvt_pk_bf16_f32 v90, v173, v172
	v_cvt_pk_bf16_f32 v86, v107, v106
	v_cvt_pk_bf16_f32 v99, v167, v166
	v_cvt_pk_bf16_f32 v95, v101, v100
	v_cvt_pk_bf16_f32 v91, v169, v168
	s_andn2_b64 vcc, exec, s[6:7]
	v_cvt_pk_bf16_f32 v87, v103, v102
	s_cbranch_vccnz .LBB0_197
	s_mul_i32 s2, s13, 0x4400
	v_add_u32_e32 v240, s2, v67
	v_add_u32_e32 v236, 0x8800, v240
	v_add_u32_e32 v237, 0x9800, v240
	v_add_u32_e32 v238, 0xa800, v240
	v_add_u32_e32 v239, 0xb800, v240
	ds_read2_b64 v[212:215], v236 offset1:2
	ds_read2_b64 v[216:219], v236 offset0:4 offset1:6
	ds_read2_b64 v[220:223], v236 offset0:8 offset1:10
	ds_read2_b64 v[224:227], v236 offset0:12 offset1:14
	s_waitcnt lgkmcnt(2)
	v_mfma_f32_32x32x16_bf16 v[50:65], v[212:215], v[96:99], v[50:65]
	v_mfma_f32_32x32x16_bf16 v[50:65], v[216:219], v[92:95], v[50:65]
	ds_read2_b64 v[212:215], v237 offset0:32 offset1:34
	ds_read2_b64 v[216:219], v237 offset0:36 offset1:38
	s_waitcnt lgkmcnt(2)
	v_mfma_f32_32x32x16_bf16 v[50:65], v[220:223], v[88:91], v[50:65]
	v_mfma_f32_32x32x16_bf16 v[50:65], v[224:227], v[84:87], v[50:65]
	ds_read2_b64 v[220:223], v237 offset0:40 offset1:42
	ds_read2_b64 v[224:227], v237 offset0:44 offset1:46
	s_waitcnt lgkmcnt(2)
	v_mfma_f32_32x32x16_bf16 v[34:49], v[212:215], v[96:99], v[34:49]
	v_mfma_f32_32x32x16_bf16 v[34:49], v[216:219], v[92:95], v[34:49]
	ds_read2_b64 v[212:215], v238 offset0:64 offset1:66
	ds_read2_b64 v[216:219], v238 offset0:68 offset1:70
	s_waitcnt lgkmcnt(2)
	v_mfma_f32_32x32x16_bf16 v[34:49], v[220:223], v[88:91], v[34:49]
	v_mfma_f32_32x32x16_bf16 v[34:49], v[224:227], v[84:87], v[34:49]
	ds_read2_b64 v[220:223], v238 offset0:72 offset1:74
	ds_read2_b64 v[224:227], v238 offset0:76 offset1:78
	s_waitcnt lgkmcnt(2)
	v_mfma_f32_32x32x16_bf16 v[18:33], v[212:215], v[96:99], v[18:33]
	v_mfma_f32_32x32x16_bf16 v[18:33], v[216:219], v[92:95], v[18:33]
	ds_read2_b64 v[212:215], v239 offset0:96 offset1:98
	ds_read2_b64 v[216:219], v239 offset0:100 offset1:102
	s_waitcnt lgkmcnt(2)
	v_mfma_f32_32x32x16_bf16 v[18:33], v[220:223], v[88:91], v[18:33]
	v_mfma_f32_32x32x16_bf16 v[18:33], v[224:227], v[84:87], v[18:33]
	ds_read2_b64 v[220:223], v239 offset0:104 offset1:106
	ds_read2_b64 v[224:227], v239 offset0:108 offset1:110
	s_waitcnt lgkmcnt(2)
	v_mfma_f32_32x32x16_bf16 v[2:17], v[212:215], v[96:99], v[2:17]
	v_mfma_f32_32x32x16_bf16 v[2:17], v[216:219], v[92:95], v[2:17]
	s_waitcnt lgkmcnt(0)
	v_mfma_f32_32x32x16_bf16 v[2:17], v[220:223], v[88:91], v[2:17]
	v_mfma_f32_32x32x16_bf16 v[2:17], v[224:227], v[84:87], v[2:17]

; template <int MODE>
; DI void attn_unit(LAS unsigned char* lds, const bf16_t* Qg, int ldq, const bf16_t* Kg, int ldk, const bf16_t* VTg, int ldvt, bf16_t* Og, int ldo,
;                   int q0, int NT, const float* gout, const float* relb, float lam, float osc, const float* qgain) {
;     ...
;         if (t + 1 < NT) AT_LSTORE(cur ^ 1, vnext);
;         __syncthreads();
;         vcur = vnext;
.LBB0_198:
	s_add_i32 s2, s13, 1
	s_cmp_lg_u32 s13, 2
	s_cselect_b32 s13, s2, 0
	s_andn2_b64 vcc, exec, s[8:9]
	s_cbranch_vccnz .LBB0_181
	s_cmp_eq_u32 s10, 0
	s_cselect_b32 s2, 0x4400, 0
	v_add3_u32 v0, s2, v192, v193
	s_waitcnt vmcnt(0) lgkmcnt(0)
	ds_write_b128 v0, v[132:135]
.LBB0_201:
	v_add3_u32 v0, s2, v189, v190
	ds_write_b128 v0, v[136:139]
	s_branch .LBB0_180
